# v48: v41 + attention loop code shifted by 4 bytes (fetch phase of the hand-written blocks)
# speedup vs baseline: 1.0042x; 1.0042x over previous
; __device__ __forceinline__ void attn_phase(LAS unsigned char* lds, const bf16_t* Q, const bf16_t* KN, const bf16_t* P, const bf16_t* VT, bf16_t* CAT, int bid, int G, const int tid) {
;     ...
;         const int rnd = u >> 8, c = u & 255, bh = c >> 1, half = c & 1;
;         const int qb = half ? (rnd == 0 ? 5 : rnd == 1 ? 2 : rnd == 2 ? 4 : 3) : (rnd == 0 ? 7 : rnd == 1 ? 0 : rnd == 2 ? 6 : 1);
;         const int b = bh >> 3, hh = bh & 7, nt = 4 * (qb + 1);
;         const size_t tok0 = (size_t)b * SEQ;
;         const int qlo = qb * 256 + 32 * w;
;         bf16x8 qf[2][6];
; #pragma unroll
;         for (int qi = 0; qi < 2; ++qi)
; #pragma unroll
;             for (int ch = 0; ch < 6; ++ch) qf[qi][ch] = *(const bf16x8*)(Q + (tok0 + qlo + 16 * qi + fr) * QW + hh * 192 + ch * 32 + fq * 8);
;         f32x4 o[8][2];
; #pragma unroll
;         for (int d = 0; d < 8; ++d) { o[d][0] = (f32x4){0.f, 0.f, 0.f, 0.f}; o[d][1] = (f32x4){0.f, 0.f, 0.f, 0.f}; }
;         float mrow[2] = {-INFINITY, -INFINITY}, lrow[2] = {0.f, 0.f};
;         const int kkey0 = tid >> 4, kc16 = tid & 15;
;         const int pkey = tid >> 3, pc8 = tid & 7;
;         const int vd0 = tid >> 3, vc8 = tid & 7;
;         const bf16_t* gk = KN + (tok0 + kkey0) * 1024 + hh * 128 + kc16 * 8;
;         const bf16_t* gp = P + (tok0 + pkey) * P_LD + OFF_KPE + pc8 * 8;
;         const bf16_t* gv = VT + (size_t)(hh * 128 + vd0) * M + tok0 + vc8 * 8;
;         const int lk = (kkey0 * KS + kc16 * 8) * 2, lp = (pkey * KS + 128 + pc8 * 8) * 2, lv = KBYTES + (vd0 * VS + vc8 * 8) * 2;
;         u32x4 rk0, rk1, rp, rv0, rv1;
;         rk0 = *(const u32x4*)(gk); rk1 = *(const u32x4*)(gk + 32 * 1024); rp = *(const u32x4*)(gp);
;         rv0 = *(const u32x4*)(gv); rv1 = *(const u32x4*)(gv + (size_t)64 * M);
.LBB0_143:
	s_nop 0
	s_bfe_u32 s4, s13, 0x4000b
	s_bfe_u32 s30, s17, 0x30001
	v_mad_u64_u32 v[164:165], s[4:5], s4, v232, v[194:195]
	s_lshl_b32 s20, s30, 7
	s_lshl_b32 s4, s13, 11
	v_add_u32_e32 v0, s20, v188
	s_and_b32 s5, s4, 0x3c00000
	s_lshl_b32 s4, s30, 8
	v_ashrrev_i32_e32 v1, 31, v0
	s_or_b32 s26, s4, s5
	v_lshlrev_b64 v[0:1], 16, v[0:1]
	s_lshl_b32 s5, s13, 1
	v_or_b32_e32 v2, v192, v0
	s_and_b32 s5, s5, 0xf000
	s_lshl_b32 s34, s38, 8
	v_or_b32_e32 v168, s5, v2
	s_lshl_b32 s5, s17, 7
	s_add_i32 s21, s34, s3
	v_lshl_add_u64 v[166:167], s[26:27], 0, v[196:197]
	s_and_b32 s26, s5, 0x7800
	s_ashr_i32 s5, s21, 31
	s_add_u32 s31, s21, s26
	v_or_b32_e32 v200, s31, v178
	s_mulk_i32 s30, 0x180
	s_mov_b32 s31, s27
	v_lshl_add_u64 v[2:3], v[184:185], 0, s[30:31]
	s_addc_u32 s5, s5, 0
	v_mad_u64_u32 v[2:3], s[30:31], v200, s9, v[2:3]
	v_mad_i32_i24 v3, s5, v233, v3
	s_mov_b64 s[30:31], 0xc000
	flat_load_dwordx4 v[104:107], v[2:3]
	flat_load_dwordx4 v[92:95], v[2:3] offset:64
	flat_load_dwordx4 v[88:91], v[2:3] offset:128
	flat_load_dwordx4 v[76:79], v[2:3] offset:192
	flat_load_dwordx4 v[72:75], v[2:3] offset:256
	flat_load_dwordx4 v[64:67], v[2:3] offset:320
	v_lshl_add_u64 v[4:5], v[2:3], 0, s[30:31]
	v_add_co_u32_e32 v2, vcc, s73, v2
	v_readlane_b32 s38, v255, 4
	s_nop 0
	v_addc_co_u32_e32 v3, vcc, 0, v3, vcc
	flat_load_dwordx4 v[108:111], v[2:3]
	flat_load_dwordx4 v[100:103], v[4:5] offset:64
	flat_load_dwordx4 v[96:99], v[4:5] offset:128
	flat_load_dwordx4 v[84:87], v[4:5] offset:192
	flat_load_dwordx4 v[80:83], v[4:5] offset:256
	flat_load_dwordx4 v[68:71], v[4:5] offset:320
	v_lshl_add_u64 v[2:3], s[26:27], 0, v[186:187]
	v_lshlrev_b64 v[2:3], 11, v[2:3]
	v_readlane_b32 s39, v255, 5
	v_mov_b32_e32 v201, s5
	s_mov_b32 s5, s27
	v_lshl_add_u64 v[2:3], s[38:39], 0, v[2:3]
	v_lshl_add_u64 v[2:3], v[2:3], 0, s[4:5]
	v_lshl_add_u64 v[2:3], v[2:3], 0, v[176:177]
	v_add_u32_e32 v6, s26, v188
	v_mov_b64_e32 v[4:5], s[10:11]
	v_mad_i64_i32 v[4:5], s[4:5], v6, s48, v[4:5]
	v_mov_b32_e32 v199, v177
	flat_load_dwordx4 v[112:115], v[2:3]
	v_add_co_u32_e32 v2, vcc, 0x10000, v2
	v_mov_b32_e32 v169, v1
	v_lshl_add_u64 v[4:5], v[4:5], 0, v[198:199]
	v_lshl_add_u64 v[0:1], s[54:55], 0, v[0:1]
	s_lshl_b32 s26, s26, 1
	v_addc_co_u32_e32 v3, vcc, 0, v3, vcc
	v_lshl_add_u64 v[0:1], v[0:1], 0, s[26:27]
	flat_load_dwordx4 v[116:119], v[2:3]
	v_add_co_u32_e32 v2, vcc, 0x1000, v4
	v_lshl_add_u64 v[0:1], v[0:1], 0, v[198:199]
	s_nop 0
	v_addc_co_u32_e32 v3, vcc, 0, v5, vcc
	flat_load_dwordx4 v[120:123], v[2:3] offset:2176
	flat_load_dwordx4 v[124:127], v[0:1]
	v_add_co_u32_e32 v0, vcc, 0x400000, v0
	v_mov_b32_e32 v28, v177
	s_nop 0
	v_addc_co_u32_e32 v1, vcc, 0, v1, vcc
	flat_load_dwordx4 v[128:131], v[0:1]
	v_mov_b32_e32 v29, v177
	v_mov_b32_e32 v30, v177
	v_mov_b32_e32 v31, v177
	v_or_b32_e32 v244, s21, v178
	v_mov_b64_e32 v[62:63], v[30:31]
	v_mov_b64_e32 v[24:25], v[28:29]
	v_mov_b64_e32 v[58:59], v[30:31]
	v_mov_b64_e32 v[20:21], v[28:29]
	v_mov_b64_e32 v[50:51], v[30:31]
	v_mov_b64_e32 v[16:17], v[28:29]
	v_mov_b64_e32 v[54:55], v[30:31]
	v_mov_b64_e32 v[12:13], v[28:29]
	v_mov_b64_e32 v[46:47], v[30:31]
	v_mov_b64_e32 v[8:9], v[28:29]
	v_mov_b64_e32 v[42:43], v[30:31]
	v_mov_b64_e32 v[4:5], v[28:29]
	v_mov_b64_e32 v[38:39], v[30:31]
	v_mov_b64_e32 v[0:1], v[28:29]
	v_mov_b64_e32 v[34:35], v[30:31]
	s_mov_b32 s30, 0
	s_or_b32 s26, s21, 31
	v_or_b32_e32 v199, 16, v244
	s_or_b32 s31, s34, 0xc0
	v_mov_b32_e32 v202, v177
	v_mov_b32_e32 v203, v177
	v_mov_b32_e32 v206, 0xff800000
	v_mov_b64_e32 v[60:61], v[28:29]
	v_mov_b64_e32 v[26:27], v[30:31]
	v_mov_b64_e32 v[56:57], v[28:29]
	v_mov_b64_e32 v[22:23], v[30:31]
	v_mov_b64_e32 v[48:49], v[28:29]
	v_mov_b64_e32 v[18:19], v[30:31]
	v_mov_b64_e32 v[52:53], v[28:29]
	v_mov_b64_e32 v[14:15], v[30:31]
	v_mov_b64_e32 v[44:45], v[28:29]
	v_mov_b64_e32 v[10:11], v[30:31]
	v_mov_b64_e32 v[40:41], v[28:29]
	v_mov_b64_e32 v[6:7], v[30:31]
	v_mov_b64_e32 v[36:37], v[28:29]
	v_mov_b64_e32 v[2:3], v[30:31]
	v_mov_b64_e32 v[32:33], v[28:29]
	v_mov_b32_e32 v207, 0xff800000
	s_mov_b32 s34, 0
	s_branch .LBB0_146
